# residual-add GEMM epilogues with 12 row loads in flight per thread (re-test on the current best)
# baseline (speedup 1.0000x reference)
;     __device__ __forceinline__ void operator()(AccT acc, const Unit& u, int wr, int wc, int fr, int fq) const {
;         const int row0 = u.pm * BM + wr * 64 + fr, col0 = u.pn * BM + wc * 32 + 4 * fq;
; #pragma unroll
;         for (int ai = 0; ai < 2; ++ai)
; #pragma unroll
;             for (int m = 0; m < 4; ++m) { const size_t off = (size_t)(row0 + ai * HALF + m * 16) * D_ + col0;
; #pragma unroll
;                 for (int bj = 0; bj < 2; ++bj)
; #pragma unroll
;                     for (int n = 0; n < 2; ++n) { const f32x4 bs = *(const f32x4*)(xin + off + bj * HALF + n * 16); *(f32x4*)(xout + off + bj * HALF + n * 16) = bs + acc[ai][bj][m][n] * scale; }
;                 asm volatile("" ::: "memory"); }
.LBB0_49:
	v_lshl_add_u32 v20, s58, 8, v166
	v_lshl_or_b32 v18, s59, 8, v179
	v_ashrrev_i32_e32 v21, 31, v20
	v_ashrrev_i32_e32 v19, 31, v18
	v_lshlrev_b64 v[26:27], 12, v[20:21]
	v_lshl_add_u64 v[28:29], s[78:79], 0, v[26:27]
	v_lshlrev_b64 v[26:27], 2, v[18:19]
	v_lshl_add_u64 v[18:19], v[28:29], 0, v[26:27]
	global_load_dwordx4 v[182:185], v[18:19], off
	global_load_dwordx4 v[186:189], v[18:19], off offset:64
	global_load_dwordx4 v[190:193], v[18:19], off offset:512
	global_load_dwordx4 v[194:197], v[18:19], off offset:576
	s_mov_b64 s[18:19], 0x10000
	v_lshl_add_u64 v[26:27], v[18:19], 0, s[18:19]
	global_load_dwordx4 v[198:201], v[26:27], off
	global_load_dwordx4 v[202:205], v[26:27], off offset:64
	global_load_dwordx4 v[206:209], v[26:27], off offset:512
	global_load_dwordx4 v[210:213], v[26:27], off offset:576
	s_mov_b64 s[18:19], 0x20000
	v_lshl_add_u64 v[26:27], v[18:19], 0, s[18:19]
	global_load_dwordx4 v[214:217], v[26:27], off
	global_load_dwordx4 v[218:221], v[26:27], off offset:64
	global_load_dwordx4 v[222:225], v[26:27], off offset:512
	global_load_dwordx4 v[226:229], v[26:27], off offset:576
	s_waitcnt vmcnt(8)
	v_pk_add_f32 v[182:183], v[164:165], v[182:183]
	v_pk_add_f32 v[184:185], v[162:163], v[184:185]
	v_pk_add_f32 v[186:187], v[156:157], v[186:187]
	v_pk_add_f32 v[188:189], v[154:155], v[188:189]
	v_pk_add_f32 v[190:191], v[160:161], v[190:191]
	v_pk_add_f32 v[192:193], v[158:159], v[192:193]
	v_pk_add_f32 v[194:195], v[128:129], v[194:195]
	v_pk_add_f32 v[196:197], v[126:127], v[196:197]
	global_store_dwordx4 v[18:19], v[182:185], off
	global_store_dwordx4 v[18:19], v[186:189], off offset:64
	global_store_dwordx4 v[18:19], v[190:193], off offset:512
	global_store_dwordx4 v[18:19], v[194:197], off offset:576
	s_nop 0
	s_mov_b64 s[18:19], 0x30000
	v_lshl_add_u64 v[26:27], v[18:19], 0, s[18:19]
	global_load_dwordx4 v[182:185], v[26:27], off
	global_load_dwordx4 v[186:189], v[26:27], off offset:64
	global_load_dwordx4 v[190:193], v[26:27], off offset:512
	global_load_dwordx4 v[194:197], v[26:27], off offset:576
	s_waitcnt vmcnt(12)
	v_pk_add_f32 v[198:199], v[124:125], v[198:199]
	v_pk_add_f32 v[200:201], v[122:123], v[200:201]
	v_pk_add_f32 v[202:203], v[114:115], v[202:203]
	v_pk_add_f32 v[204:205], v[116:117], v[204:205]
	v_pk_add_f32 v[206:207], v[120:121], v[206:207]
	v_pk_add_f32 v[208:209], v[118:119], v[208:209]
	v_pk_add_f32 v[210:211], v[112:113], v[210:211]
	v_pk_add_f32 v[212:213], v[110:111], v[212:213]
	s_mov_b64 s[18:19], 0x10000
	v_lshl_add_u64 v[20:21], v[18:19], 0, s[18:19]
	global_store_dwordx4 v[20:21], v[198:201], off
	global_store_dwordx4 v[20:21], v[202:205], off offset:64
	global_store_dwordx4 v[20:21], v[206:209], off offset:512
	global_store_dwordx4 v[20:21], v[210:213], off offset:576
	s_nop 0
	s_mov_b64 s[18:19], 0x80000
	v_lshl_add_u64 v[26:27], v[18:19], 0, s[18:19]
	global_load_dwordx4 v[198:201], v[26:27], off
	global_load_dwordx4 v[202:205], v[26:27], off offset:64
	global_load_dwordx4 v[206:209], v[26:27], off offset:512
	global_load_dwordx4 v[210:213], v[26:27], off offset:576
	s_waitcnt vmcnt(16)
	v_pk_add_f32 v[214:215], v[106:107], v[214:215]
	v_pk_add_f32 v[216:217], v[108:109], v[216:217]
	v_pk_add_f32 v[218:219], v[98:99], v[218:219]
	v_pk_add_f32 v[220:221], v[100:101], v[220:221]
	v_pk_add_f32 v[222:223], v[104:105], v[222:223]
	v_pk_add_f32 v[224:225], v[102:103], v[224:225]
	v_pk_add_f32 v[226:227], v[96:97], v[226:227]
	v_pk_add_f32 v[228:229], v[94:95], v[228:229]
	s_mov_b64 s[18:19], 0x20000
	v_lshl_add_u64 v[20:21], v[18:19], 0, s[18:19]
	global_store_dwordx4 v[20:21], v[214:217], off
	global_store_dwordx4 v[20:21], v[218:221], off offset:64
	global_store_dwordx4 v[20:21], v[222:225], off offset:512
	global_store_dwordx4 v[20:21], v[226:229], off offset:576
	s_nop 0
	s_mov_b64 s[18:19], 0x90000
	v_lshl_add_u64 v[26:27], v[18:19], 0, s[18:19]
	global_load_dwordx4 v[214:217], v[26:27], off
	global_load_dwordx4 v[218:221], v[26:27], off offset:64
	global_load_dwordx4 v[222:225], v[26:27], off offset:512
	global_load_dwordx4 v[226:229], v[26:27], off offset:576
	s_waitcnt vmcnt(16)
;     __device__ __forceinline__ void operator()(AccT acc, const Unit& u, int wr, int wc, int fr, int fq) const {
;     ...
;             for (int m = 0; m < 4; ++m) { const size_t off = (size_t)(row0 + ai * HALF + m * 16) * D_ + col0;
; #pragma unroll
;                 for (int bj = 0; bj < 2; ++bj)
; #pragma unroll
;                     for (int n = 0; n < 2; ++n) { const f32x4 bs = *(const f32x4*)(xin + off + bj * HALF + n * 16); *(f32x4*)(xout + off + bj * HALF + n * 16) = bs + acc[ai][bj][m][n] * scale; }
;                 asm volatile("" ::: "memory"); }
	v_pk_add_f32 v[182:183], v[90:91], v[182:183]
	v_pk_add_f32 v[184:185], v[92:93], v[184:185]
	v_pk_add_f32 v[186:187], v[82:83], v[186:187]
	v_pk_add_f32 v[188:189], v[84:85], v[188:189]
	v_pk_add_f32 v[190:191], v[88:89], v[190:191]
	v_pk_add_f32 v[192:193], v[86:87], v[192:193]
	v_pk_add_f32 v[194:195], v[80:81], v[194:195]
	v_pk_add_f32 v[196:197], v[78:79], v[196:197]
	s_mov_b64 s[18:19], 0x30000
	v_lshl_add_u64 v[20:21], v[18:19], 0, s[18:19]
	global_store_dwordx4 v[20:21], v[182:185], off
	global_store_dwordx4 v[20:21], v[186:189], off offset:64
	global_store_dwordx4 v[20:21], v[190:193], off offset:512
	global_store_dwordx4 v[20:21], v[194:197], off offset:576
	s_nop 0
	s_mov_b64 s[18:19], 0xa0000
	v_lshl_add_u64 v[26:27], v[18:19], 0, s[18:19]
	global_load_dwordx4 v[182:185], v[26:27], off
	global_load_dwordx4 v[186:189], v[26:27], off offset:64
	global_load_dwordx4 v[190:193], v[26:27], off offset:512
	global_load_dwordx4 v[194:197], v[26:27], off offset:576
	s_waitcnt vmcnt(16)
	v_pk_add_f32 v[198:199], v[76:77], v[198:199]
	v_pk_add_f32 v[200:201], v[74:75], v[200:201]
	v_pk_add_f32 v[202:203], v[68:69], v[202:203]
	v_pk_add_f32 v[204:205], v[66:67], v[204:205]
	v_pk_add_f32 v[206:207], v[72:73], v[206:207]
	v_pk_add_f32 v[208:209], v[70:71], v[208:209]
	v_pk_add_f32 v[210:211], v[64:65], v[210:211]
	v_pk_add_f32 v[212:213], v[62:63], v[212:213]
	s_mov_b64 s[18:19], 0x80000
	v_lshl_add_u64 v[20:21], v[18:19], 0, s[18:19]
	global_store_dwordx4 v[20:21], v[198:201], off
	global_store_dwordx4 v[20:21], v[202:205], off offset:64
	global_store_dwordx4 v[20:21], v[206:209], off offset:512
	global_store_dwordx4 v[20:21], v[210:213], off offset:576
	s_nop 0
	s_mov_b64 s[18:19], 0xb0000
	v_lshl_add_u64 v[26:27], v[18:19], 0, s[18:19]
	global_load_dwordx4 v[198:201], v[26:27], off
	global_load_dwordx4 v[202:205], v[26:27], off offset:64
	global_load_dwordx4 v[206:209], v[26:27], off offset:512
	global_load_dwordx4 v[210:213], v[26:27], off offset:576
	s_waitcnt vmcnt(16)
	v_pk_add_f32 v[214:215], v[60:61], v[214:215]
	v_pk_add_f32 v[216:217], v[58:59], v[216:217]
	v_pk_add_f32 v[218:219], v[50:51], v[218:219]
	v_pk_add_f32 v[220:221], v[52:53], v[220:221]
	v_pk_add_f32 v[222:223], v[56:57], v[222:223]
	v_pk_add_f32 v[224:225], v[54:55], v[224:225]
	v_pk_add_f32 v[226:227], v[48:49], v[226:227]
	v_pk_add_f32 v[228:229], v[46:47], v[228:229]
	s_mov_b64 s[18:19], 0x90000
	v_lshl_add_u64 v[20:21], v[18:19], 0, s[18:19]
	global_store_dwordx4 v[20:21], v[214:217], off
	global_store_dwordx4 v[20:21], v[218:221], off offset:64
	global_store_dwordx4 v[20:21], v[222:225], off offset:512
	global_store_dwordx4 v[20:21], v[226:229], off offset:576
	s_waitcnt vmcnt(12)
	v_pk_add_f32 v[182:183], v[40:41], v[182:183]
	v_pk_add_f32 v[184:185], v[38:39], v[184:185]
	v_pk_add_f32 v[186:187], v[32:33], v[186:187]
	v_pk_add_f32 v[188:189], v[30:31], v[188:189]
	v_pk_add_f32 v[190:191], v[36:37], v[190:191]
	v_pk_add_f32 v[192:193], v[34:35], v[192:193]
	v_pk_add_f32 v[194:195], v[24:25], v[194:195]
	v_pk_add_f32 v[196:197], v[22:23], v[196:197]
	s_mov_b64 s[18:19], 0xa0000
	v_lshl_add_u64 v[20:21], v[18:19], 0, s[18:19]
	global_store_dwordx4 v[20:21], v[182:185], off
	global_store_dwordx4 v[20:21], v[186:189], off offset:64
	global_store_dwordx4 v[20:21], v[190:193], off offset:512
	global_store_dwordx4 v[20:21], v[194:197], off offset:576
	s_waitcnt vmcnt(8)
	v_pk_add_f32 v[198:199], v[16:17], v[198:199]
	v_pk_add_f32 v[200:201], v[14:15], v[200:201]
	v_pk_add_f32 v[202:203], v[12:13], v[202:203]
	v_pk_add_f32 v[204:205], v[10:11], v[204:205]
	v_pk_add_f32 v[206:207], v[6:7], v[206:207]
	v_pk_add_f32 v[208:209], v[8:9], v[208:209]
	v_pk_add_f32 v[210:211], v[2:3], v[210:211]
	v_pk_add_f32 v[212:213], v[4:5], v[212:213]
	s_mov_b64 s[18:19], 0xb0000
	v_lshl_add_u64 v[20:21], v[18:19], 0, s[18:19]
	global_store_dwordx4 v[20:21], v[198:201], off
	global_store_dwordx4 v[20:21], v[202:205], off offset:64
	global_store_dwordx4 v[20:21], v[206:209], off offset:512
	global_store_dwordx4 v[20:21], v[210:213], off offset:576
	s_mov_b64 s[18:19], -1
	s_and_b64 vcc, exec, s[2:3]
	s_cbranch_vccnz .LBB0_32
	s_andn2_b64 vcc, exec, s[10:11]
	s_cbranch_vccnz .LBB0_31
	s_barrier
	s_branch .LBB0_31

;     __device__ __forceinline__ void operator()(AccT acc, const Unit& u, int wr, int wc, int fr, int fq) const {
;         const int row0 = u.pm * BM + wr * 64 + fr, col0 = u.pn * BM + wc * 32 + 4 * fq;
; #pragma unroll
;         for (int ai = 0; ai < 2; ++ai)
; #pragma unroll
;             for (int m = 0; m < 4; ++m) { const size_t off = (size_t)(row0 + ai * HALF + m * 16) * D_ + col0;
; #pragma unroll
;                 for (int bj = 0; bj < 2; ++bj)
; #pragma unroll
;                     for (int n = 0; n < 2; ++n) { const f32x4 bs = *(const f32x4*)(xin + off + bj * HALF + n * 16); *(f32x4*)(xout + off + bj * HALF + n * 16) = bs + acc[ai][bj][m][n] * scale; }
;                 asm volatile("" ::: "memory"); }
.LBB0_109:
	v_lshl_add_u32 v156, s58, 8, v160
	v_lshl_or_b32 v138, s59, 8, v162
	v_ashrrev_i32_e32 v157, 31, v156
	v_ashrrev_i32_e32 v139, 31, v138
	v_lshlrev_b64 v[154:155], 12, v[156:157]
	v_lshl_add_u64 v[154:155], s[78:79], 0, v[154:155]
	v_lshlrev_b64 v[158:159], 2, v[138:139]
	v_lshl_add_u64 v[154:155], v[154:155], 0, v[158:159]
	global_load_dwordx4 v[184:187], v[154:155], off
	global_load_dwordx4 v[188:191], v[154:155], off offset:64
	global_load_dwordx4 v[192:195], v[154:155], off offset:512
	global_load_dwordx4 v[196:199], v[154:155], off offset:576
	s_mov_b64 s[18:19], 0x10000
	v_lshl_add_u64 v[232:233], v[154:155], 0, s[18:19]
	global_load_dwordx4 v[200:203], v[232:233], off
	global_load_dwordx4 v[204:207], v[232:233], off offset:64
	global_load_dwordx4 v[208:211], v[232:233], off offset:512
	global_load_dwordx4 v[212:215], v[232:233], off offset:576
	s_mov_b64 s[18:19], 0x20000
	v_lshl_add_u64 v[232:233], v[154:155], 0, s[18:19]
	global_load_dwordx4 v[216:219], v[232:233], off
	global_load_dwordx4 v[220:223], v[232:233], off offset:64
	global_load_dwordx4 v[224:227], v[232:233], off offset:512
	global_load_dwordx4 v[228:231], v[232:233], off offset:576
	s_waitcnt vmcnt(8)
	v_pk_add_f32 v[184:185], v[126:127], v[184:185]
	v_pk_add_f32 v[186:187], v[128:129], v[186:187]
	v_pk_add_f32 v[188:189], v[122:123], v[188:189]
	v_pk_add_f32 v[190:191], v[124:125], v[190:191]
	v_pk_add_f32 v[192:193], v[118:119], v[192:193]
	v_pk_add_f32 v[194:195], v[120:121], v[194:195]
	v_pk_add_f32 v[196:197], v[114:115], v[196:197]
	v_pk_add_f32 v[198:199], v[116:117], v[198:199]
	global_store_dwordx4 v[154:155], v[184:187], off
	global_store_dwordx4 v[154:155], v[188:191], off offset:64
	global_store_dwordx4 v[154:155], v[192:195], off offset:512
	global_store_dwordx4 v[154:155], v[196:199], off offset:576
	s_nop 0
	s_mov_b64 s[18:19], 0x30000
	v_lshl_add_u64 v[232:233], v[154:155], 0, s[18:19]
	global_load_dwordx4 v[184:187], v[232:233], off
	global_load_dwordx4 v[188:191], v[232:233], off offset:64
	global_load_dwordx4 v[192:195], v[232:233], off offset:512
	global_load_dwordx4 v[196:199], v[232:233], off offset:576
	s_waitcnt vmcnt(12)
	v_pk_add_f32 v[200:201], v[110:111], v[200:201]
	v_pk_add_f32 v[202:203], v[112:113], v[202:203]
	v_pk_add_f32 v[204:205], v[106:107], v[204:205]
	v_pk_add_f32 v[206:207], v[108:109], v[206:207]
	v_pk_add_f32 v[208:209], v[102:103], v[208:209]
	v_pk_add_f32 v[210:211], v[104:105], v[210:211]
	v_pk_add_f32 v[212:213], v[98:99], v[212:213]
	v_pk_add_f32 v[214:215], v[100:101], v[214:215]
	s_mov_b64 s[18:19], 0x10000
	v_lshl_add_u64 v[234:235], v[154:155], 0, s[18:19]
	global_store_dwordx4 v[234:235], v[200:203], off
	global_store_dwordx4 v[234:235], v[204:207], off offset:64
	global_store_dwordx4 v[234:235], v[208:211], off offset:512
	global_store_dwordx4 v[234:235], v[212:215], off offset:576
	s_nop 0
	s_mov_b64 s[18:19], 0x80000
	v_lshl_add_u64 v[232:233], v[154:155], 0, s[18:19]
	global_load_dwordx4 v[200:203], v[232:233], off
	global_load_dwordx4 v[204:207], v[232:233], off offset:64
	global_load_dwordx4 v[208:211], v[232:233], off offset:512
	global_load_dwordx4 v[212:215], v[232:233], off offset:576
	s_waitcnt vmcnt(16)
	v_pk_add_f32 v[216:217], v[94:95], v[216:217]
	v_pk_add_f32 v[218:219], v[96:97], v[218:219]
	v_pk_add_f32 v[220:221], v[90:91], v[220:221]
	v_pk_add_f32 v[222:223], v[92:93], v[222:223]
	v_pk_add_f32 v[224:225], v[86:87], v[224:225]
	v_pk_add_f32 v[226:227], v[88:89], v[226:227]
	v_pk_add_f32 v[228:229], v[82:83], v[228:229]
	v_pk_add_f32 v[230:231], v[84:85], v[230:231]
	s_mov_b64 s[18:19], 0x20000
	v_lshl_add_u64 v[234:235], v[154:155], 0, s[18:19]
	global_store_dwordx4 v[234:235], v[216:219], off
	global_store_dwordx4 v[234:235], v[220:223], off offset:64
	global_store_dwordx4 v[234:235], v[224:227], off offset:512
	global_store_dwordx4 v[234:235], v[228:231], off offset:576
	s_nop 0
	s_mov_b64 s[18:19], 0x90000
	v_lshl_add_u64 v[232:233], v[154:155], 0, s[18:19]
	global_load_dwordx4 v[216:219], v[232:233], off
	global_load_dwordx4 v[220:223], v[232:233], off offset:64
	global_load_dwordx4 v[224:227], v[232:233], off offset:512
	global_load_dwordx4 v[228:231], v[232:233], off offset:576
	s_waitcnt vmcnt(16)
;     __device__ __forceinline__ void operator()(AccT acc, const Unit& u, int wr, int wc, int fr, int fq) const {
;     ...
;             for (int m = 0; m < 4; ++m) { const size_t off = (size_t)(row0 + ai * HALF + m * 16) * D_ + col0;
; #pragma unroll
;                 for (int bj = 0; bj < 2; ++bj)
; #pragma unroll
;                     for (int n = 0; n < 2; ++n) { const f32x4 bs = *(const f32x4*)(xin + off + bj * HALF + n * 16); *(f32x4*)(xout + off + bj * HALF + n * 16) = bs + acc[ai][bj][m][n] * scale; }
;                 asm volatile("" ::: "memory"); }
	v_pk_add_f32 v[184:185], v[78:79], v[184:185]
	v_pk_add_f32 v[186:187], v[80:81], v[186:187]
	v_pk_add_f32 v[188:189], v[74:75], v[188:189]
	v_pk_add_f32 v[190:191], v[76:77], v[190:191]
	v_pk_add_f32 v[192:193], v[70:71], v[192:193]
	v_pk_add_f32 v[194:195], v[72:73], v[194:195]
	v_pk_add_f32 v[196:197], v[66:67], v[196:197]
	v_pk_add_f32 v[198:199], v[68:69], v[198:199]
	s_mov_b64 s[18:19], 0x30000
	v_lshl_add_u64 v[234:235], v[154:155], 0, s[18:19]
	global_store_dwordx4 v[234:235], v[184:187], off
	global_store_dwordx4 v[234:235], v[188:191], off offset:64
	global_store_dwordx4 v[234:235], v[192:195], off offset:512
	global_store_dwordx4 v[234:235], v[196:199], off offset:576
	s_nop 0
	s_mov_b64 s[18:19], 0xa0000
	v_lshl_add_u64 v[232:233], v[154:155], 0, s[18:19]
	global_load_dwordx4 v[184:187], v[232:233], off
	global_load_dwordx4 v[188:191], v[232:233], off offset:64
	global_load_dwordx4 v[192:195], v[232:233], off offset:512
	global_load_dwordx4 v[196:199], v[232:233], off offset:576
	s_waitcnt vmcnt(16)
	v_pk_add_f32 v[200:201], v[62:63], v[200:201]
	v_pk_add_f32 v[202:203], v[64:65], v[202:203]
	v_pk_add_f32 v[204:205], v[58:59], v[204:205]
	v_pk_add_f32 v[206:207], v[60:61], v[206:207]
	v_pk_add_f32 v[208:209], v[54:55], v[208:209]
	v_pk_add_f32 v[210:211], v[56:57], v[210:211]
	v_pk_add_f32 v[212:213], v[50:51], v[212:213]
	v_pk_add_f32 v[214:215], v[52:53], v[214:215]
	s_mov_b64 s[18:19], 0x80000
	v_lshl_add_u64 v[234:235], v[154:155], 0, s[18:19]
	global_store_dwordx4 v[234:235], v[200:203], off
	global_store_dwordx4 v[234:235], v[204:207], off offset:64
	global_store_dwordx4 v[234:235], v[208:211], off offset:512
	global_store_dwordx4 v[234:235], v[212:215], off offset:576
	s_nop 0
	s_mov_b64 s[18:19], 0xb0000
	v_lshl_add_u64 v[232:233], v[154:155], 0, s[18:19]
	global_load_dwordx4 v[200:203], v[232:233], off
	global_load_dwordx4 v[204:207], v[232:233], off offset:64
	global_load_dwordx4 v[208:211], v[232:233], off offset:512
	global_load_dwordx4 v[212:215], v[232:233], off offset:576
	s_waitcnt vmcnt(16)
	v_pk_add_f32 v[216:217], v[46:47], v[216:217]
	v_pk_add_f32 v[218:219], v[48:49], v[218:219]
	v_pk_add_f32 v[220:221], v[42:43], v[220:221]
	v_pk_add_f32 v[222:223], v[44:45], v[222:223]
	v_pk_add_f32 v[224:225], v[38:39], v[224:225]
	v_pk_add_f32 v[226:227], v[40:41], v[226:227]
	v_pk_add_f32 v[228:229], v[34:35], v[228:229]
	v_pk_add_f32 v[230:231], v[36:37], v[230:231]
	s_mov_b64 s[18:19], 0x90000
	v_lshl_add_u64 v[234:235], v[154:155], 0, s[18:19]
	global_store_dwordx4 v[234:235], v[216:219], off
	global_store_dwordx4 v[234:235], v[220:223], off offset:64
	global_store_dwordx4 v[234:235], v[224:227], off offset:512
	global_store_dwordx4 v[234:235], v[228:231], off offset:576
	s_waitcnt vmcnt(12)
	v_pk_add_f32 v[184:185], v[30:31], v[184:185]
	v_pk_add_f32 v[186:187], v[32:33], v[186:187]
	v_pk_add_f32 v[188:189], v[26:27], v[188:189]
	v_pk_add_f32 v[190:191], v[28:29], v[190:191]
	v_pk_add_f32 v[192:193], v[22:23], v[192:193]
	v_pk_add_f32 v[194:195], v[24:25], v[194:195]
	v_pk_add_f32 v[196:197], v[18:19], v[196:197]
	v_pk_add_f32 v[198:199], v[20:21], v[198:199]
	s_mov_b64 s[18:19], 0xa0000
	v_lshl_add_u64 v[234:235], v[154:155], 0, s[18:19]
	global_store_dwordx4 v[234:235], v[184:187], off
	global_store_dwordx4 v[234:235], v[188:191], off offset:64
	global_store_dwordx4 v[234:235], v[192:195], off offset:512
	global_store_dwordx4 v[234:235], v[196:199], off offset:576
	s_waitcnt vmcnt(8)
	v_pk_add_f32 v[200:201], v[14:15], v[200:201]
	v_pk_add_f32 v[202:203], v[16:17], v[202:203]
	v_pk_add_f32 v[204:205], v[10:11], v[204:205]
	v_pk_add_f32 v[206:207], v[12:13], v[206:207]
	v_pk_add_f32 v[208:209], v[6:7], v[208:209]
	v_pk_add_f32 v[210:211], v[8:9], v[210:211]
	v_pk_add_f32 v[212:213], v[2:3], v[212:213]
	v_pk_add_f32 v[214:215], v[4:5], v[214:215]
	s_mov_b64 s[18:19], 0xb0000
	v_lshl_add_u64 v[234:235], v[154:155], 0, s[18:19]
	global_store_dwordx4 v[234:235], v[200:203], off
	global_store_dwordx4 v[234:235], v[204:207], off offset:64
	global_store_dwordx4 v[234:235], v[208:211], off offset:512
	global_store_dwordx4 v[234:235], v[212:215], off offset:576
	s_mov_b64 s[18:19], -1
	s_and_b64 vcc, exec, s[2:3]
	s_cbranch_vccnz .LBB0_93
	s_andn2_b64 vcc, exec, s[10:11]
	s_cbranch_vccnz .LBB0_92
	s_barrier
	s_branch .LBB0_92

;     __device__ __forceinline__ void operator()(AccT acc, const Unit& u, int wr, int wc, int fr, int fq) const {
;         const int row0 = u.pm * BM + wr * 64 + fr, col0 = u.pn * BM + wc * 32 + 4 * fq;
; #pragma unroll
;         for (int ai = 0; ai < 2; ++ai)
; #pragma unroll
;             for (int m = 0; m < 4; ++m) { const size_t off = (size_t)(row0 + ai * HALF + m * 16) * D_ + col0;
; #pragma unroll
;                 for (int bj = 0; bj < 2; ++bj)
; #pragma unroll
;                     for (int n = 0; n < 2; ++n) { const f32x4 bs = *(const f32x4*)(xin + off + bj * HALF + n * 16); *(f32x4*)(xout + off + bj * HALF + n * 16) = bs + acc[ai][bj][m][n] * scale; }
;                 asm volatile("" ::: "memory"); }
.LBB0_634:
	v_lshl_add_u32 v26, s58, 8, v166
	v_lshl_or_b32 v20, s59, 8, v179
	v_ashrrev_i32_e32 v27, 31, v26
	v_ashrrev_i32_e32 v21, 31, v20
	v_lshlrev_b64 v[18:19], 10, v[26:27]
	v_lshl_add_u64 v[18:19], v[18:19], 0, v[20:21]
	v_readlane_b32 s20, v254, 29
	v_lshlrev_b64 v[18:19], 2, v[18:19]
	v_readlane_b32 s21, v254, 30
	s_mov_b64 s[18:19], 0x80000
	s_and_b64 vcc, exec, s[2:3]
	v_lshl_add_u64 v[28:29], s[20:21], 0, v[18:19]
	v_lshl_add_u64 v[230:231], s[78:79], 0, v[18:19]
	global_load_dwordx4 v[182:185], v[28:29], off
	global_load_dwordx4 v[186:189], v[28:29], off offset:64
	global_load_dwordx4 v[190:193], v[28:29], off offset:512
	global_load_dwordx4 v[194:197], v[28:29], off offset:576
	s_mov_b64 s[18:19], 0x10000
	v_lshl_add_u64 v[26:27], v[28:29], 0, s[18:19]
	global_load_dwordx4 v[198:201], v[26:27], off
	global_load_dwordx4 v[202:205], v[26:27], off offset:64
	global_load_dwordx4 v[206:209], v[26:27], off offset:512
	global_load_dwordx4 v[210:213], v[26:27], off offset:576
	s_mov_b64 s[18:19], 0x20000
	v_lshl_add_u64 v[26:27], v[28:29], 0, s[18:19]
	global_load_dwordx4 v[214:217], v[26:27], off
	global_load_dwordx4 v[218:221], v[26:27], off offset:64
	global_load_dwordx4 v[222:225], v[26:27], off offset:512
	global_load_dwordx4 v[226:229], v[26:27], off offset:576
	s_waitcnt vmcnt(8)
	v_pk_add_f32 v[182:183], v[164:165], v[182:183]
	v_pk_add_f32 v[184:185], v[162:163], v[184:185]
	v_pk_add_f32 v[186:187], v[126:127], v[186:187]
	v_pk_add_f32 v[188:189], v[128:129], v[188:189]
	v_pk_add_f32 v[190:191], v[158:159], v[190:191]
	v_pk_add_f32 v[192:193], v[160:161], v[192:193]
	v_pk_add_f32 v[194:195], v[156:157], v[194:195]
	v_pk_add_f32 v[196:197], v[154:155], v[196:197]
	global_store_dwordx4 v[230:231], v[182:185], off
	global_store_dwordx4 v[230:231], v[186:189], off offset:64
	global_store_dwordx4 v[230:231], v[190:193], off offset:512
	global_store_dwordx4 v[230:231], v[194:197], off offset:576
	s_nop 0
	s_mov_b64 s[18:19], 0x30000
	v_lshl_add_u64 v[26:27], v[28:29], 0, s[18:19]
	global_load_dwordx4 v[182:185], v[26:27], off
	global_load_dwordx4 v[186:189], v[26:27], off offset:64
	global_load_dwordx4 v[190:193], v[26:27], off offset:512
	global_load_dwordx4 v[194:197], v[26:27], off offset:576
	s_waitcnt vmcnt(12)
	v_pk_add_f32 v[198:199], v[124:125], v[198:199]
	v_pk_add_f32 v[200:201], v[122:123], v[200:201]
	v_pk_add_f32 v[202:203], v[110:111], v[202:203]
	v_pk_add_f32 v[204:205], v[112:113], v[204:205]
	v_pk_add_f32 v[206:207], v[118:119], v[206:207]
	v_pk_add_f32 v[208:209], v[120:121], v[208:209]
	v_pk_add_f32 v[210:211], v[116:117], v[210:211]
	v_pk_add_f32 v[212:213], v[114:115], v[212:213]
	s_mov_b64 s[18:19], 0x10000
	v_lshl_add_u64 v[20:21], v[230:231], 0, s[18:19]
	global_store_dwordx4 v[20:21], v[198:201], off
	global_store_dwordx4 v[20:21], v[202:205], off offset:64
	global_store_dwordx4 v[20:21], v[206:209], off offset:512
	global_store_dwordx4 v[20:21], v[210:213], off offset:576
	s_nop 0
	s_mov_b64 s[18:19], 0x80000
	v_lshl_add_u64 v[26:27], v[28:29], 0, s[18:19]
	global_load_dwordx4 v[198:201], v[26:27], off
	global_load_dwordx4 v[202:205], v[26:27], off offset:64
	global_load_dwordx4 v[206:209], v[26:27], off offset:512
	global_load_dwordx4 v[210:213], v[26:27], off offset:576
	s_waitcnt vmcnt(16)
	v_pk_add_f32 v[214:215], v[106:107], v[214:215]
	v_pk_add_f32 v[216:217], v[108:109], v[216:217]
	v_pk_add_f32 v[218:219], v[94:95], v[218:219]
	v_pk_add_f32 v[220:221], v[96:97], v[220:221]
	v_pk_add_f32 v[222:223], v[102:103], v[222:223]
	v_pk_add_f32 v[224:225], v[104:105], v[224:225]
	v_pk_add_f32 v[226:227], v[100:101], v[226:227]
	v_pk_add_f32 v[228:229], v[98:99], v[228:229]
	s_mov_b64 s[18:19], 0x20000
	v_lshl_add_u64 v[20:21], v[230:231], 0, s[18:19]
	global_store_dwordx4 v[20:21], v[214:217], off
	global_store_dwordx4 v[20:21], v[218:221], off offset:64
	global_store_dwordx4 v[20:21], v[222:225], off offset:512
	global_store_dwordx4 v[20:21], v[226:229], off offset:576
	s_nop 0
	s_mov_b64 s[18:19], 0x90000
	v_lshl_add_u64 v[26:27], v[28:29], 0, s[18:19]
	global_load_dwordx4 v[214:217], v[26:27], off
	global_load_dwordx4 v[218:221], v[26:27], off offset:64
	global_load_dwordx4 v[222:225], v[26:27], off offset:512
	global_load_dwordx4 v[226:229], v[26:27], off offset:576
	s_waitcnt vmcnt(16)
;     __device__ __forceinline__ void operator()(AccT acc, const Unit& u, int wr, int wc, int fr, int fq) const {
;     ...
;             for (int m = 0; m < 4; ++m) { const size_t off = (size_t)(row0 + ai * HALF + m * 16) * D_ + col0;
; #pragma unroll
;                 for (int bj = 0; bj < 2; ++bj)
; #pragma unroll
;                     for (int n = 0; n < 2; ++n) { const f32x4 bs = *(const f32x4*)(xin + off + bj * HALF + n * 16); *(f32x4*)(xout + off + bj * HALF + n * 16) = bs + acc[ai][bj][m][n] * scale; }
;                 asm volatile("" ::: "memory"); }
	v_pk_add_f32 v[182:183], v[90:91], v[182:183]
	v_pk_add_f32 v[184:185], v[92:93], v[184:185]
	v_pk_add_f32 v[186:187], v[78:79], v[186:187]
	v_pk_add_f32 v[188:189], v[80:81], v[188:189]
	v_pk_add_f32 v[190:191], v[86:87], v[190:191]
	v_pk_add_f32 v[192:193], v[88:89], v[192:193]
	v_pk_add_f32 v[194:195], v[84:85], v[194:195]
	v_pk_add_f32 v[196:197], v[82:83], v[196:197]
	s_mov_b64 s[18:19], 0x30000
	v_lshl_add_u64 v[20:21], v[230:231], 0, s[18:19]
	global_store_dwordx4 v[20:21], v[182:185], off
	global_store_dwordx4 v[20:21], v[186:189], off offset:64
	global_store_dwordx4 v[20:21], v[190:193], off offset:512
	global_store_dwordx4 v[20:21], v[194:197], off offset:576
	s_nop 0
	s_mov_b64 s[18:19], 0xa0000
	v_lshl_add_u64 v[26:27], v[28:29], 0, s[18:19]
	global_load_dwordx4 v[182:185], v[26:27], off
	global_load_dwordx4 v[186:189], v[26:27], off offset:64
	global_load_dwordx4 v[190:193], v[26:27], off offset:512
	global_load_dwordx4 v[194:197], v[26:27], off offset:576
	s_waitcnt vmcnt(16)
	v_pk_add_f32 v[198:199], v[76:77], v[198:199]
	v_pk_add_f32 v[200:201], v[74:75], v[200:201]
	v_pk_add_f32 v[202:203], v[62:63], v[202:203]
	v_pk_add_f32 v[204:205], v[64:65], v[204:205]
	v_pk_add_f32 v[206:207], v[70:71], v[206:207]
	v_pk_add_f32 v[208:209], v[72:73], v[208:209]
	v_pk_add_f32 v[210:211], v[68:69], v[210:211]
	v_pk_add_f32 v[212:213], v[66:67], v[212:213]
	s_mov_b64 s[18:19], 0x80000
	v_lshl_add_u64 v[20:21], v[230:231], 0, s[18:19]
	global_store_dwordx4 v[20:21], v[198:201], off
	global_store_dwordx4 v[20:21], v[202:205], off offset:64
	global_store_dwordx4 v[20:21], v[206:209], off offset:512
	global_store_dwordx4 v[20:21], v[210:213], off offset:576
	s_nop 0
	s_mov_b64 s[18:19], 0xb0000
	v_lshl_add_u64 v[26:27], v[28:29], 0, s[18:19]
	global_load_dwordx4 v[198:201], v[26:27], off
	global_load_dwordx4 v[202:205], v[26:27], off offset:64
	global_load_dwordx4 v[206:209], v[26:27], off offset:512
	global_load_dwordx4 v[210:213], v[26:27], off offset:576
	s_waitcnt vmcnt(16)
	v_pk_add_f32 v[214:215], v[60:61], v[214:215]
	v_pk_add_f32 v[216:217], v[58:59], v[216:217]
	v_pk_add_f32 v[218:219], v[46:47], v[218:219]
	v_pk_add_f32 v[220:221], v[48:49], v[220:221]
	v_pk_add_f32 v[222:223], v[54:55], v[222:223]
	v_pk_add_f32 v[224:225], v[56:57], v[224:225]
	v_pk_add_f32 v[226:227], v[52:53], v[226:227]
	v_pk_add_f32 v[228:229], v[50:51], v[228:229]
	s_mov_b64 s[18:19], 0x90000
	v_lshl_add_u64 v[20:21], v[230:231], 0, s[18:19]
	global_store_dwordx4 v[20:21], v[214:217], off
	global_store_dwordx4 v[20:21], v[218:221], off offset:64
	global_store_dwordx4 v[20:21], v[222:225], off offset:512
	global_store_dwordx4 v[20:21], v[226:229], off offset:576
	s_waitcnt vmcnt(12)
	v_pk_add_f32 v[182:183], v[40:41], v[182:183]
	v_pk_add_f32 v[184:185], v[38:39], v[184:185]
	v_pk_add_f32 v[186:187], v[22:23], v[186:187]
	v_pk_add_f32 v[188:189], v[24:25], v[188:189]
	v_pk_add_f32 v[190:191], v[34:35], v[190:191]
	v_pk_add_f32 v[192:193], v[36:37], v[192:193]
	v_pk_add_f32 v[194:195], v[32:33], v[194:195]
	v_pk_add_f32 v[196:197], v[30:31], v[196:197]
	s_mov_b64 s[18:19], 0xa0000
	v_lshl_add_u64 v[20:21], v[230:231], 0, s[18:19]
	global_store_dwordx4 v[20:21], v[182:185], off
	global_store_dwordx4 v[20:21], v[186:189], off offset:64
	global_store_dwordx4 v[20:21], v[190:193], off offset:512
	global_store_dwordx4 v[20:21], v[194:197], off offset:576
	s_waitcnt vmcnt(8)
	v_pk_add_f32 v[198:199], v[16:17], v[198:199]
	v_pk_add_f32 v[200:201], v[14:15], v[200:201]
	v_pk_add_f32 v[202:203], v[10:11], v[202:203]
	v_pk_add_f32 v[204:205], v[12:13], v[204:205]
	v_pk_add_f32 v[206:207], v[6:7], v[206:207]
	v_pk_add_f32 v[208:209], v[8:9], v[208:209]
	v_pk_add_f32 v[210:211], v[2:3], v[210:211]
	v_pk_add_f32 v[212:213], v[4:5], v[212:213]
	s_mov_b64 s[18:19], 0xb0000
	v_lshl_add_u64 v[20:21], v[230:231], 0, s[18:19]
	global_store_dwordx4 v[20:21], v[198:201], off
	global_store_dwordx4 v[20:21], v[202:205], off offset:64
	global_store_dwordx4 v[20:21], v[206:209], off offset:512
	global_store_dwordx4 v[20:21], v[210:213], off offset:576
	s_mov_b64 s[18:19], -1
	s_and_b64 vcc, exec, s[2:3]
	s_cbranch_vccnz .LBB0_617
	s_andn2_b64 vcc, exec, s[10:11]
	s_cbranch_vccnz .LBB0_616
	s_barrier
	s_branch .LBB0_616
